# register-resident triangular-inverse chain (packed bf16 accumulator tiles as MFMA operands, no LDS round trips) now also in both scan pass-1 loops
# speedup vs baseline: 1.1000x; 1.0180x over previous
; __device__ __forceinline__ int mrow(int r, int hi) { return (r & 3) + 8 * (r >> 2) + 4 * hi; }
; template <int NV, bool WITHY> __device__ __forceinline__ void scan_chunk(const ScanLds& L, f32x16& st, bool hasT, int kt, int vt, int wave, int lane_, bf16* ypark = nullptr) {
;     ...
;     if (wave == 0) {
;         __builtin_amdgcn_s_setprio(3);
; #pragma unroll
;         for (int r = 0; r < 16; ++r) { Q[r] = 0.f; QT[r] = 0.f; }
;         mm32<4>(Q, L.Bt, 72, 0, L.Kap, 72, 0, l31, hi);
;         mm32<4>(QT, L.Kap, 72, 0, L.Bt, 72, 0, l31, hi);
; #pragma unroll
;         for (int r = 0; r < 16; ++r) { const int row = mrow(r, hi); Q[r] = row < l31 ? Q[r] : 0.f; QT[r] = l31 < row ? QT[r] : 0.f; W[r] = (row == l31 ? 1.f : 0.f) - QT[r]; }
;         nat_store(L.BQ, Q, l31, hi); nat_store(L.BQT, QT, l31, hi);
;         {   f32x16 Qn, QTn;
; #pragma unroll
;             for (int r = 0; r < 16; ++r) { Qn[r] = 0.f; QTn[r] = 0.f; }
;             mm32<2>(Qn, L.BQT, 40, 0, L.BQ, 40, 0, l31, hi); mm32<2>(QTn, L.BQ, 40, 0, L.BQT, 40, 0, l31, hi); Q = Qn; QT = QTn; }
.Lw0skip0:
	s_waitcnt vmcnt(21)
	s_setprio 3
	v_add3_u32 v42, s57, v35, v169
	ds_read_b128 v[34:37], v42
	ds_read_b128 v[50:53], v42 offset:32
	ds_read_b128 v[38:41], v172
	ds_read_b128 v[54:57], v172 offset:32
	ds_read_b128 v[58:61], v42 offset:64
	ds_read_b128 v[62:65], v172 offset:64
	ds_read_b128 v[66:69], v42 offset:96
	ds_read_b128 v[70:73], v172 offset:96
	s_add_i32 s0, 0, 0x16000
	s_waitcnt lgkmcnt(5)
	v_mfma_f32_32x32x16_bf16 v[18:33], v[34:37], v[38:41], 0
	v_add3_u32 v74, s0, v170, v1
	v_add3_u32 v77, 0, v170, v1
	v_mfma_f32_32x32x16_bf16 v[34:49], v[38:41], v[34:37], 0
	s_waitcnt lgkmcnt(4)
	v_mfma_f32_32x32x16_bf16 v[34:49], v[54:57], v[50:53], v[34:49]
	v_mfma_f32_32x32x16_bf16 v[18:33], v[50:53], v[54:57], v[18:33]
	v_lshlrev_b32_e32 v50, 2, v168
	v_cmp_lt_i32_e64 s[52:53], v166, v50
	v_cmp_lt_i32_e32 vcc, v50, v166
	v_or_b32_e32 v56, 2, v50
	v_or_b32_e32 v55, 3, v50
	s_waitcnt lgkmcnt(2)
	v_mfma_f32_32x32x16_bf16 v[34:49], v[62:65], v[58:61], v[34:49]
	v_mfma_f32_32x32x16_bf16 v[18:33], v[58:61], v[62:65], v[18:33]
	s_waitcnt lgkmcnt(0)
	v_mfma_f32_32x32x16_bf16 v[34:49], v[70:73], v[66:69], v[34:49]
	v_mfma_f32_32x32x16_bf16 v[18:33], v[66:69], v[70:73], v[18:33]
	s_nop 10
	v_cndmask_b32_e64 v52, 0, v34, s[52:53]
	v_cmp_eq_u32_e64 s[52:53], v50, v166
	v_or_b32_e32 v34, 1, v50
	v_cndmask_b32_e64 v54, v35, 0, vcc
	v_cndmask_b32_e32 v51, 0, v18, vcc
	v_cndmask_b32_e64 v18, 0, 1.0, s[52:53]
	v_cmp_lt_i32_e64 s[52:53], v34, v166
	v_cmp_eq_u32_e32 vcc, v34, v166
	v_sub_f32_e32 v18, v18, v52
	v_cndmask_b32_e64 v53, 0, v19, s[52:53]
	v_cndmask_b32_e64 v19, 0, 1.0, vcc
	v_cmp_lt_i32_e32 vcc, v56, v166
	v_cmp_lt_i32_e64 s[52:53], v166, v55
	v_sub_f32_e32 v19, v19, v54
	v_cndmask_b32_e32 v57, 0, v20, vcc
	v_cmp_lt_i32_e32 vcc, v166, v56
	v_cndmask_b32_e64 v35, 0, v37, s[52:53]
	v_cmp_eq_u32_e64 s[52:53], v55, v166
	v_cndmask_b32_e32 v34, 0, v36, vcc
	v_cmp_lt_i32_e32 vcc, v55, v166
	v_add_u32_e32 v55, 9, v50
	s_nop 0
	v_cndmask_b32_e32 v58, 0, v21, vcc
	v_cmp_eq_u32_e32 vcc, v56, v166
	v_add_u32_e32 v56, 8, v50
	v_cndmask_b32_e64 v21, 0, 1.0, s[52:53]
	v_cndmask_b32_e64 v20, 0, 1.0, vcc
	v_cmp_lt_i32_e32 vcc, v56, v166
	v_cmp_lt_i32_e64 s[52:53], v166, v55
	v_pk_add_f32 v[20:21], v[20:21], v[34:35] neg_lo:[0,1] neg_hi:[0,1]
	v_cndmask_b32_e32 v59, 0, v22, vcc
	v_cmp_lt_i32_e32 vcc, v166, v56
	v_cndmask_b32_e64 v37, 0, v39, s[52:53]
	v_cmp_eq_u32_e64 s[52:53], v55, v166
	v_cndmask_b32_e32 v36, 0, v38, vcc
	v_cmp_lt_i32_e32 vcc, v55, v166
	v_add_u32_e32 v55, 11, v50
	s_nop 0
	v_cndmask_b32_e32 v60, 0, v23, vcc
	v_cmp_eq_u32_e32 vcc, v56, v166
	v_add_u32_e32 v56, 10, v50
	v_cndmask_b32_e64 v23, 0, 1.0, s[52:53]
	v_cndmask_b32_e64 v22, 0, 1.0, vcc
	v_cmp_lt_i32_e32 vcc, v56, v166
	v_cmp_lt_i32_e64 s[52:53], v166, v55
	v_pk_add_f32 v[22:23], v[22:23], v[36:37] neg_lo:[0,1] neg_hi:[0,1]
	v_cndmask_b32_e32 v61, 0, v24, vcc
	v_cmp_lt_i32_e32 vcc, v166, v56
	v_cndmask_b32_e64 v39, 0, v41, s[52:53]
	v_cmp_eq_u32_e64 s[52:53], v55, v166
	v_cndmask_b32_e32 v38, 0, v40, vcc
	v_cmp_lt_i32_e32 vcc, v55, v166
	v_add_u32_e32 v55, 17, v50
	s_nop 0
	v_cndmask_b32_e32 v62, 0, v25, vcc
	v_cmp_eq_u32_e32 vcc, v56, v166
	v_add_u32_e32 v56, 16, v50
	v_cndmask_b32_e64 v25, 0, 1.0, s[52:53]
	v_cndmask_b32_e64 v24, 0, 1.0, vcc
	v_cmp_lt_i32_e32 vcc, v56, v166
	v_cmp_lt_i32_e64 s[52:53], v166, v55
	v_pk_add_f32 v[24:25], v[24:25], v[38:39] neg_lo:[0,1] neg_hi:[0,1]
	v_cndmask_b32_e32 v63, 0, v26, vcc
	v_cmp_lt_i32_e32 vcc, v166, v56
	v_cndmask_b32_e64 v41, 0, v43, s[52:53]
	v_cmp_eq_u32_e64 s[52:53], v55, v166
	v_cndmask_b32_e32 v40, 0, v42, vcc
	v_cmp_lt_i32_e32 vcc, v55, v166
	v_add_u32_e32 v55, 19, v50
	s_nop 0
	v_cndmask_b32_e32 v64, 0, v27, vcc
	v_cmp_eq_u32_e32 vcc, v56, v166
	v_add_u32_e32 v56, 18, v50
	v_cndmask_b32_e64 v27, 0, 1.0, s[52:53]
	v_cndmask_b32_e64 v26, 0, 1.0, vcc
	v_cmp_lt_i32_e32 vcc, v56, v166
	v_cmp_lt_i32_e64 s[52:53], v166, v55
	v_pk_add_f32 v[26:27], v[26:27], v[40:41] neg_lo:[0,1] neg_hi:[0,1]
	v_cndmask_b32_e32 v65, 0, v28, vcc
	v_cmp_lt_i32_e32 vcc, v166, v56
	v_cndmask_b32_e64 v43, 0, v45, s[52:53]
	v_cmp_eq_u32_e64 s[52:53], v55, v166
	v_cndmask_b32_e32 v42, 0, v44, vcc
	v_cmp_lt_i32_e32 vcc, v55, v166
	v_add_u32_e32 v55, 25, v50
	s_nop 0
	v_cndmask_b32_e32 v66, 0, v29, vcc
	v_cmp_eq_u32_e32 vcc, v56, v166
	v_add_u32_e32 v56, 24, v50
	v_cndmask_b32_e64 v29, 0, 1.0, s[52:53]
	v_cndmask_b32_e64 v28, 0, 1.0, vcc
	v_cmp_lt_i32_e32 vcc, v56, v166
	v_cmp_lt_i32_e64 s[52:53], v166, v55
	v_pk_add_f32 v[28:29], v[28:29], v[42:43] neg_lo:[0,1] neg_hi:[0,1]
	v_cndmask_b32_e32 v67, 0, v30, vcc
	v_cmp_lt_i32_e32 vcc, v166, v56
	v_cndmask_b32_e64 v45, 0, v47, s[52:53]
	v_cmp_eq_u32_e64 s[52:53], v55, v166
	v_cndmask_b32_e32 v44, 0, v46, vcc
	v_cmp_lt_i32_e32 vcc, v55, v166
	v_add_u32_e32 v55, 27, v50
	v_add_u32_e32 v50, 26, v50
	v_cndmask_b32_e32 v68, 0, v31, vcc
	v_cmp_eq_u32_e32 vcc, v56, v166
	v_cndmask_b32_e64 v31, 0, 1.0, s[52:53]
	v_cmp_lt_i32_e64 s[52:53], v166, v55
	v_cndmask_b32_e64 v30, 0, 1.0, vcc
	v_cmp_lt_i32_e32 vcc, v50, v166
	v_cndmask_b32_e64 v47, 0, v49, s[52:53]
	v_cvt_pk_bf16_f32 v49, v57, v58
	v_cndmask_b32_e32 v56, 0, v32, vcc
	v_cmp_lt_i32_e32 vcc, v166, v50
	v_cmp_eq_u32_e64 s[52:53], v55, v166
	v_pk_add_f32 v[30:31], v[30:31], v[44:45] neg_lo:[0,1] neg_hi:[0,1]
	v_cndmask_b32_e32 v46, 0, v48, vcc
	v_cvt_pk_bf16_f32 v48, v51, v53
	v_cmp_lt_i32_e32 vcc, v55, v166
	v_mov_b64_e32 v[246:247], v[48:49]
	v_cvt_pk_bf16_f32 v48, v59, v60
	v_cvt_pk_bf16_f32 v49, v61, v62
	v_cndmask_b32_e32 v69, 0, v33, vcc
	v_mov_b64_e32 v[248:249], v[48:49]
	v_cvt_pk_bf16_f32 v250, v63, v64
	v_cvt_pk_bf16_f32 v251, v65, v66
	v_cvt_pk_bf16_f32 v252, v67, v68
	v_cvt_pk_bf16_f32 v253, v56, v69
	v_cvt_pk_bf16_f32 v49, v34, v35
	v_cvt_pk_bf16_f32 v76, v36, v37
	v_cvt_pk_bf16_f32 v77, v38, v39
	v_cvt_pk_bf16_f32 v34, v40, v41
	v_cvt_pk_bf16_f32 v35, v42, v43
	v_cvt_pk_bf16_f32 v48, v52, v54
	v_mov_b64_e32 v[78:79], v[34:35]
	v_cvt_pk_bf16_f32 v34, v44, v45
	v_cvt_pk_bf16_f32 v35, v46, v47
	v_mov_b64_e32 v[74:75], v[48:49]
	v_mov_b64_e32 v[80:81], v[34:35]
	v_cmp_eq_u32_e32 vcc, v50, v166
	v_cndmask_b32_e64 v33, 0, 1.0, s[52:53]
	v_cndmask_b32_e64 v32, 0, 1.0, vcc
	v_pk_add_f32 v[32:33], v[32:33], v[46:47] neg_lo:[0,1] neg_hi:[0,1]
	s_waitcnt lgkmcnt(1)
; template <int NV, bool WITHY> __device__ __forceinline__ void scan_chunk(const ScanLds& L, f32x16& st, bool hasT, int kt, int vt, int wave, int lane_, bf16* ypark = nullptr) {
;     ...
; #pragma unroll
;         for (int n = 1; n < 3; ++n) {
;             nat_store(L.BQ, Q, l31, hi); nat_store(L.BQT, QT, l31, hi); nat_store(L.BW, W, l31, hi);
;             f32x16 Qn, QTn;
; #pragma unroll
;             for (int r = 0; r < 16; ++r) { Qn[r] = 0.f; QTn[r] = 0.f; }
;             mm32<2>(W, L.BQ, 40, 0, L.BW, 40, 0, l31, hi); mm32<2>(Qn, L.BQT, 40, 0, L.BQ, 40, 0, l31, hi); mm32<2>(QTn, L.BQ, 40, 0, L.BQT, 40, 0, l31, hi); Q = Qn; QT = QTn; }
	v_mfma_f32_32x32x16_bf16 v[34:49], v[74:77], v[246:249], 0
	v_mfma_f32_32x32x16_bf16 v[50:65], v[246:249], v[74:77], 0
	s_waitcnt lgkmcnt(0)
	v_mfma_f32_32x32x16_bf16 v[34:49], v[78:81], v[250:253], v[34:49]
	v_mfma_f32_32x32x16_bf16 v[50:65], v[250:253], v[78:81], v[50:65]
	s_nop 10
	v_cvt_pk_bf16_f32 v246, v34, v35
	v_cvt_pk_bf16_f32 v247, v36, v37
	v_cvt_pk_bf16_f32 v248, v38, v39
	v_cvt_pk_bf16_f32 v249, v40, v41
	v_cvt_pk_bf16_f32 v250, v42, v43
	v_cvt_pk_bf16_f32 v251, v44, v45
	v_cvt_pk_bf16_f32 v252, v46, v47
	v_cvt_pk_bf16_f32 v253, v48, v49
	v_cvt_pk_bf16_f32 v74, v50, v51
	v_cvt_pk_bf16_f32 v75, v52, v53
	v_cvt_pk_bf16_f32 v76, v54, v55
	v_cvt_pk_bf16_f32 v77, v56, v57
	v_cvt_pk_bf16_f32 v78, v58, v59
	v_cvt_pk_bf16_f32 v79, v60, v61
	v_cvt_pk_bf16_f32 v80, v62, v63
	v_cvt_pk_bf16_f32 v81, v64, v65
	v_cvt_pk_bf16_f32 v66, v18, v19
	v_cvt_pk_bf16_f32 v67, v20, v21
	v_cvt_pk_bf16_f32 v68, v22, v23
	v_cvt_pk_bf16_f32 v69, v24, v25
	v_cvt_pk_bf16_f32 v70, v26, v27
	v_cvt_pk_bf16_f32 v71, v28, v29
	v_cvt_pk_bf16_f32 v72, v30, v31
	v_cvt_pk_bf16_f32 v73, v32, v33
	s_waitcnt lgkmcnt(1)
	v_mfma_f32_32x32x16_bf16 v[18:33], v[246:249], v[66:69], v[18:33]
	s_waitcnt lgkmcnt(2)
	v_mfma_f32_32x32x16_bf16 v[18:33], v[250:253], v[70:73], v[18:33]
	s_waitcnt lgkmcnt(1)
	v_mfma_f32_32x32x16_bf16 v[50:65], v[74:77], v[246:249], 0
	v_mfma_f32_32x32x16_bf16 v[34:49], v[246:249], v[74:77], 0
	s_waitcnt lgkmcnt(0)
	v_mfma_f32_32x32x16_bf16 v[34:49], v[250:253], v[78:81], v[34:49]
	v_mfma_f32_32x32x16_bf16 v[50:65], v[78:81], v[250:253], v[50:65]
	s_nop 10
	v_cvt_pk_bf16_f32 v74, v34, v35
	v_cvt_pk_bf16_f32 v75, v36, v37
	v_cvt_pk_bf16_f32 v76, v38, v39
	v_cvt_pk_bf16_f32 v77, v40, v41
	v_cvt_pk_bf16_f32 v78, v42, v43
	v_cvt_pk_bf16_f32 v79, v44, v45
	v_cvt_pk_bf16_f32 v34, v46, v47
	v_cvt_pk_bf16_f32 v35, v48, v49
	v_cvt_pk_bf16_f32 v50, v50, v51
	v_cvt_pk_bf16_f32 v51, v52, v53
	v_mov_b64_e32 v[80:81], v[34:35]
	v_cvt_pk_bf16_f32 v34, v18, v19
	v_cvt_pk_bf16_f32 v35, v20, v21
	v_mov_b64_e32 v[246:247], v[50:51]
	v_cvt_pk_bf16_f32 v50, v54, v55
	v_cvt_pk_bf16_f32 v51, v56, v57
	v_mov_b64_e32 v[66:67], v[34:35]
	v_cvt_pk_bf16_f32 v34, v22, v23
	v_cvt_pk_bf16_f32 v35, v24, v25
	v_mov_b64_e32 v[248:249], v[50:51]
	v_cvt_pk_bf16_f32 v50, v58, v59
	v_cvt_pk_bf16_f32 v51, v60, v61
	v_mov_b64_e32 v[68:69], v[34:35]
	v_cvt_pk_bf16_f32 v34, v26, v27
	v_cvt_pk_bf16_f32 v35, v28, v29
	v_mov_b64_e32 v[250:251], v[50:51]
	v_cvt_pk_bf16_f32 v50, v62, v63
	v_cvt_pk_bf16_f32 v51, v64, v65
	v_mov_b64_e32 v[70:71], v[34:35]
	v_cvt_pk_bf16_f32 v34, v30, v31
	v_cvt_pk_bf16_f32 v35, v32, v33
	v_mov_b64_e32 v[252:253], v[50:51]
	v_mov_b64_e32 v[72:73], v[34:35]
	s_waitcnt lgkmcnt(1)
	v_mfma_f32_32x32x16_bf16 v[18:33], v[246:249], v[66:69], v[18:33]
	s_waitcnt lgkmcnt(2)
	v_mfma_f32_32x32x16_bf16 v[18:33], v[250:253], v[70:73], v[18:33]
	s_waitcnt lgkmcnt(1)
	v_mfma_f32_32x32x16_bf16 v[50:65], v[74:77], v[246:249], 0
	v_mfma_f32_32x32x16_bf16 v[34:49], v[246:249], v[74:77], 0
	s_waitcnt lgkmcnt(0)
	v_mfma_f32_32x32x16_bf16 v[50:65], v[78:81], v[250:253], v[50:65]
	v_mfma_f32_32x32x16_bf16 v[34:49], v[250:253], v[78:81], v[34:49]

; __device__ __forceinline__ unsigned f2bf(float f) { return pk2(f, f) & 0xffffu; }
; __device__ __forceinline__ int mrow(int r, int hi) { return (r & 3) + 8 * (r >> 2) + 4 * hi; }
; template <int NV, bool WITHY> __device__ __forceinline__ void scan_chunk(const ScanLds& L, f32x16& st, bool hasT, int kt, int vt, int wave, int lane_, bf16* ypark = nullptr) {
;     ...
;     if (wave == 0) {
; #pragma unroll
;         for (int n = 3; n < 5; ++n) {
;             nat_store(L.BQ, Q, l31, hi); if (n < 4) nat_store(L.BQT, QT, l31, hi); nat_store(L.BW, W, l31, hi);
;             f32x16 Qn, QTn;
; #pragma unroll
;             for (int r = 0; r < 16; ++r) { Qn[r] = 0.f; QTn[r] = 0.f; }
;             mm32<2>(W, L.BQ, 40, 0, L.BW, 40, 0, l31, hi);
;             if (n < 4) { mm32<2>(Qn, L.BQT, 40, 0, L.BQ, 40, 0, l31, hi); mm32<2>(QTn, L.BQ, 40, 0, L.BQT, 40, 0, l31, hi); Q = Qn; QT = QTn; } }
; #pragma unroll
;         for (int r = 0; r < 16; ++r) L.TiT[mrow(r, hi) * 40 + l31] = (bf16)f2bf(W[r]);
;         __builtin_amdgcn_s_setprio(0);
.LBB0_322:
	s_andn2_b64 vcc, exec, s[26:27]
	s_cbranch_vccnz .LBB0_324
	s_add_i32 s0, 0, 0x16000
	v_add3_u32 v66, s0, v170, v1
	v_cvt_pk_bf16_f32 v246, v50, v51
	v_cvt_pk_bf16_f32 v247, v52, v53
	v_cvt_pk_bf16_f32 v50, v54, v55
	v_cvt_pk_bf16_f32 v51, v56, v57
	v_cvt_pk_bf16_f32 v34, v34, v35
	v_cvt_pk_bf16_f32 v35, v36, v37
	v_cvt_pk_bf16_f32 v36, v38, v39
	v_cvt_pk_bf16_f32 v37, v40, v41
	v_mov_b64_e32 v[248:249], v[50:51]
	v_cvt_pk_bf16_f32 v50, v58, v59
	v_mov_b64_e32 v[74:75], v[34:35]
	v_mov_b64_e32 v[76:77], v[36:37]
	v_cvt_pk_bf16_f32 v34, v42, v43
	v_cvt_pk_bf16_f32 v35, v44, v45
	v_cvt_pk_bf16_f32 v36, v46, v47
	v_cvt_pk_bf16_f32 v37, v48, v49
	v_mad_u32_u24 v58, v166, s93, 0
	v_mov_b64_e32 v[78:79], v[34:35]
	v_mov_b64_e32 v[80:81], v[36:37]
	v_add_u32_e32 v59, v58, v1
	v_cvt_pk_bf16_f32 v66, v18, v19
	v_cvt_pk_bf16_f32 v67, v20, v21
	v_cvt_pk_bf16_f32 v34, v22, v23
	v_cvt_pk_bf16_f32 v35, v24, v25
	v_cvt_pk_bf16_f32 v51, v60, v61
	v_mov_b64_e32 v[68:69], v[34:35]
	v_cvt_pk_bf16_f32 v34, v26, v27
	v_cvt_pk_bf16_f32 v35, v28, v29
	v_mov_b64_e32 v[250:251], v[50:51]
	v_cvt_pk_bf16_f32 v50, v62, v63
	v_cvt_pk_bf16_f32 v51, v64, v65
	v_mov_b64_e32 v[70:71], v[34:35]
	v_cvt_pk_bf16_f32 v34, v30, v31
	v_cvt_pk_bf16_f32 v35, v32, v33
	v_mov_b64_e32 v[252:253], v[50:51]
	v_mov_b64_e32 v[72:73], v[34:35]
	s_waitcnt lgkmcnt(0)
	v_mfma_f32_32x32x16_bf16 v[18:33], v[246:249], v[66:69], v[18:33]
	s_waitcnt lgkmcnt(0)
	v_mfma_f32_32x32x16_bf16 v[18:33], v[250:253], v[70:73], v[18:33]
	s_waitcnt lgkmcnt(1)
	v_mfma_f32_32x32x16_bf16 v[34:49], v[74:77], v[246:249], 0
	s_waitcnt lgkmcnt(0)
	v_mfma_f32_32x32x16_bf16 v[34:49], v[78:81], v[250:253], v[34:49]
	s_nop 11
	v_cvt_pk_bf16_f32 v246, v34, v35
	v_cvt_pk_bf16_f32 v247, v36, v37
	v_cvt_pk_bf16_f32 v248, v38, v39
	v_cvt_pk_bf16_f32 v249, v40, v41
	v_cvt_pk_bf16_f32 v250, v42, v43
	v_cvt_pk_bf16_f32 v251, v44, v45
	v_cvt_pk_bf16_f32 v252, v46, v47
	v_cvt_pk_bf16_f32 v253, v48, v49
	v_cvt_pk_bf16_f32 v66, v18, v19
	v_cvt_pk_bf16_f32 v67, v20, v21
	v_cvt_pk_bf16_f32 v68, v22, v23
	v_cvt_pk_bf16_f32 v69, v24, v25
	v_cvt_pk_bf16_f32 v70, v26, v27
	v_cvt_pk_bf16_f32 v71, v28, v29
	v_cvt_pk_bf16_f32 v72, v30, v31
	v_cvt_pk_bf16_f32 v73, v32, v33
	s_waitcnt lgkmcnt(0)
	v_mfma_f32_32x32x16_bf16 v[18:33], v[246:249], v[66:69], v[18:33]
	s_waitcnt lgkmcnt(0)
	v_mfma_f32_32x32x16_bf16 v[18:33], v[250:253], v[70:73], v[18:33]
	v_mul_i32_i24_e32 v34, 0xffffffb2, v166
	s_nop 10
	v_cvt_pk_bf16_f32 v18, v18, s0
	s_movk_i32 s0, 0x140
	v_mul_lo_u32 v35, v168, s0
	v_add3_u32 v34, v58, v34, v35
	ds_write_b16 v34, v18 offset:49664
	v_cvt_pk_bf16_f32 v18, v19, s0
	ds_write_b16 v34, v18 offset:49744
	v_cvt_pk_bf16_f32 v18, v20, s0
	ds_write_b16 v34, v18 offset:49824
	v_cvt_pk_bf16_f32 v18, v21, s0
	ds_write_b16 v34, v18 offset:49904
	v_cvt_pk_bf16_f32 v18, v22, s0
	ds_write_b16 v34, v18 offset:50304
	v_cvt_pk_bf16_f32 v18, v23, s0
	ds_write_b16 v34, v18 offset:50384
	v_cvt_pk_bf16_f32 v18, v24, s0
	ds_write_b16 v34, v18 offset:50464
	v_cvt_pk_bf16_f32 v18, v25, s0
	ds_write_b16 v34, v18 offset:50544
	v_cvt_pk_bf16_f32 v18, v26, s0
	ds_write_b16 v34, v18 offset:50944
	v_cvt_pk_bf16_f32 v18, v27, s0
	ds_write_b16 v34, v18 offset:51024
	v_cvt_pk_bf16_f32 v18, v28, s0
	ds_write_b16 v34, v18 offset:51104
	v_cvt_pk_bf16_f32 v18, v29, s0
	ds_write_b16 v34, v18 offset:51184
	v_cvt_pk_bf16_f32 v18, v30, s0
	ds_write_b16 v34, v18 offset:51584
	v_cvt_pk_bf16_f32 v18, v31, s0
	ds_write_b16 v34, v18 offset:51664
	v_cvt_pk_bf16_f32 v18, v32, s0
	ds_write_b16 v34, v18 offset:51744
	v_cvt_pk_bf16_f32 v18, v33, s0
	ds_write_b16 v34, v18 offset:51824
	s_setprio 0

; __device__ __forceinline__ int mrow(int r, int hi) { return (r & 3) + 8 * (r >> 2) + 4 * hi; }
; template <int NV, bool WITHY> __device__ __forceinline__ void scan_chunk(const ScanLds& L, f32x16& st, bool hasT, int kt, int vt, int wave, int lane_, bf16* ypark = nullptr) {
;     ...
;     if (wave == 0) {
;         __builtin_amdgcn_s_setprio(3);
; #pragma unroll
;         for (int r = 0; r < 16; ++r) { Q[r] = 0.f; QT[r] = 0.f; }
;         mm32<4>(Q, L.Bt, 72, 0, L.Kap, 72, 0, l31, hi);
;         mm32<4>(QT, L.Kap, 72, 0, L.Bt, 72, 0, l31, hi);
; #pragma unroll
;         for (int r = 0; r < 16; ++r) { const int row = mrow(r, hi); Q[r] = row < l31 ? Q[r] : 0.f; QT[r] = l31 < row ? QT[r] : 0.f; W[r] = (row == l31 ? 1.f : 0.f) - QT[r]; }
;         nat_store(L.BQ, Q, l31, hi); nat_store(L.BQT, QT, l31, hi);
;         {   f32x16 Qn, QTn;
; #pragma unroll
;             for (int r = 0; r < 16; ++r) { Qn[r] = 0.f; QTn[r] = 0.f; }
;             mm32<2>(Qn, L.BQT, 40, 0, L.BQ, 40, 0, l31, hi); mm32<2>(QTn, L.BQ, 40, 0, L.BQT, 40, 0, l31, hi); Q = Qn; QT = QTn; }
.Lw0skip1:
	s_waitcnt vmcnt(21)
	s_setprio 3
	v_add3_u32 v42, s57, v35, v169
	ds_read_b128 v[34:37], v42
	ds_read_b128 v[50:53], v42 offset:32
	ds_read_b128 v[38:41], v174
	ds_read_b128 v[54:57], v174 offset:32
	ds_read_b128 v[58:61], v42 offset:64
	ds_read_b128 v[62:65], v174 offset:64
	ds_read_b128 v[66:69], v42 offset:96
	ds_read_b128 v[70:73], v174 offset:96
	v_add_u32_e32 v74, v173, v1
	s_waitcnt lgkmcnt(5)
	v_mfma_f32_32x32x16_bf16 v[18:33], v[34:37], v[38:41], 0
	v_add_u32_e32 v75, v172, v1
	v_add_u32_e32 v76, v171, v1
	v_mfma_f32_32x32x16_bf16 v[34:49], v[38:41], v[34:37], 0
	s_waitcnt lgkmcnt(4)
	v_mfma_f32_32x32x16_bf16 v[34:49], v[54:57], v[50:53], v[34:49]
	v_mfma_f32_32x32x16_bf16 v[18:33], v[50:53], v[54:57], v[18:33]
	v_lshlrev_b32_e32 v50, 2, v168
	v_cmp_lt_i32_e64 s[54:55], v166, v50
	v_cmp_lt_i32_e32 vcc, v50, v166
	v_or_b32_e32 v56, 2, v50
	v_or_b32_e32 v55, 3, v50
	s_waitcnt lgkmcnt(2)
	v_mfma_f32_32x32x16_bf16 v[34:49], v[62:65], v[58:61], v[34:49]
	v_mfma_f32_32x32x16_bf16 v[18:33], v[58:61], v[62:65], v[18:33]
	s_waitcnt lgkmcnt(0)
	v_mfma_f32_32x32x16_bf16 v[34:49], v[70:73], v[66:69], v[34:49]
	v_mfma_f32_32x32x16_bf16 v[18:33], v[66:69], v[70:73], v[18:33]
	s_nop 10
	v_cndmask_b32_e64 v52, 0, v34, s[54:55]
	v_cmp_eq_u32_e64 s[54:55], v50, v166
	v_or_b32_e32 v34, 1, v50
	v_cndmask_b32_e64 v54, v35, 0, vcc
	v_cndmask_b32_e32 v51, 0, v18, vcc
	v_cndmask_b32_e64 v18, 0, 1.0, s[54:55]
	v_cmp_lt_i32_e64 s[54:55], v34, v166
	v_cmp_eq_u32_e32 vcc, v34, v166
	v_sub_f32_e32 v18, v18, v52
	v_cndmask_b32_e64 v53, 0, v19, s[54:55]
	v_cndmask_b32_e64 v19, 0, 1.0, vcc
	v_cmp_lt_i32_e32 vcc, v56, v166
	v_cmp_lt_i32_e64 s[54:55], v166, v55
	v_sub_f32_e32 v19, v19, v54
	v_cndmask_b32_e32 v57, 0, v20, vcc
	v_cmp_lt_i32_e32 vcc, v166, v56
	v_cndmask_b32_e64 v35, 0, v37, s[54:55]
	v_cmp_eq_u32_e64 s[54:55], v55, v166
	v_cndmask_b32_e32 v34, 0, v36, vcc
	v_cmp_lt_i32_e32 vcc, v55, v166
	v_add_u32_e32 v55, 9, v50
	s_nop 0
	v_cndmask_b32_e32 v58, 0, v21, vcc
	v_cmp_eq_u32_e32 vcc, v56, v166
	v_add_u32_e32 v56, 8, v50
	v_cndmask_b32_e64 v21, 0, 1.0, s[54:55]
	v_cndmask_b32_e64 v20, 0, 1.0, vcc
	v_cmp_lt_i32_e32 vcc, v56, v166
	v_cmp_lt_i32_e64 s[54:55], v166, v55
	v_pk_add_f32 v[20:21], v[20:21], v[34:35] neg_lo:[0,1] neg_hi:[0,1]
	v_cndmask_b32_e32 v59, 0, v22, vcc
	v_cmp_lt_i32_e32 vcc, v166, v56
	v_cndmask_b32_e64 v37, 0, v39, s[54:55]
	v_cmp_eq_u32_e64 s[54:55], v55, v166
	v_cndmask_b32_e32 v36, 0, v38, vcc
	v_cmp_lt_i32_e32 vcc, v55, v166
	v_add_u32_e32 v55, 11, v50
	s_nop 0
	v_cndmask_b32_e32 v60, 0, v23, vcc
	v_cmp_eq_u32_e32 vcc, v56, v166
	v_add_u32_e32 v56, 10, v50
	v_cndmask_b32_e64 v23, 0, 1.0, s[54:55]
	v_cndmask_b32_e64 v22, 0, 1.0, vcc
	v_cmp_lt_i32_e32 vcc, v56, v166
	v_cmp_lt_i32_e64 s[54:55], v166, v55
	v_pk_add_f32 v[22:23], v[22:23], v[36:37] neg_lo:[0,1] neg_hi:[0,1]
	v_cndmask_b32_e32 v61, 0, v24, vcc
	v_cmp_lt_i32_e32 vcc, v166, v56
	v_cndmask_b32_e64 v39, 0, v41, s[54:55]
	v_cmp_eq_u32_e64 s[54:55], v55, v166
	v_cndmask_b32_e32 v38, 0, v40, vcc
	v_cmp_lt_i32_e32 vcc, v55, v166
	v_add_u32_e32 v55, 17, v50
	s_nop 0
	v_cndmask_b32_e32 v62, 0, v25, vcc
	v_cmp_eq_u32_e32 vcc, v56, v166
	v_add_u32_e32 v56, 16, v50
	v_cndmask_b32_e64 v25, 0, 1.0, s[54:55]
	v_cndmask_b32_e64 v24, 0, 1.0, vcc
	v_cmp_lt_i32_e32 vcc, v56, v166
	v_cmp_lt_i32_e64 s[54:55], v166, v55
	v_pk_add_f32 v[24:25], v[24:25], v[38:39] neg_lo:[0,1] neg_hi:[0,1]
	v_cndmask_b32_e32 v63, 0, v26, vcc
	v_cmp_lt_i32_e32 vcc, v166, v56
	v_cndmask_b32_e64 v41, 0, v43, s[54:55]
	v_cmp_eq_u32_e64 s[54:55], v55, v166
	v_cndmask_b32_e32 v40, 0, v42, vcc
	v_cmp_lt_i32_e32 vcc, v55, v166
	v_add_u32_e32 v55, 19, v50
	s_nop 0
	v_cndmask_b32_e32 v64, 0, v27, vcc
	v_cmp_eq_u32_e32 vcc, v56, v166
	v_add_u32_e32 v56, 18, v50
	v_cndmask_b32_e64 v27, 0, 1.0, s[54:55]
	v_cndmask_b32_e64 v26, 0, 1.0, vcc
	v_cmp_lt_i32_e32 vcc, v56, v166
	v_cmp_lt_i32_e64 s[54:55], v166, v55
	v_pk_add_f32 v[26:27], v[26:27], v[40:41] neg_lo:[0,1] neg_hi:[0,1]
	v_cndmask_b32_e32 v65, 0, v28, vcc
	v_cmp_lt_i32_e32 vcc, v166, v56
	v_cndmask_b32_e64 v43, 0, v45, s[54:55]
	v_cmp_eq_u32_e64 s[54:55], v55, v166
	v_cndmask_b32_e32 v42, 0, v44, vcc
	v_cmp_lt_i32_e32 vcc, v55, v166
	v_add_u32_e32 v55, 25, v50
	s_nop 0
	v_cndmask_b32_e32 v66, 0, v29, vcc
	v_cmp_eq_u32_e32 vcc, v56, v166
	v_add_u32_e32 v56, 24, v50
	v_cndmask_b32_e64 v29, 0, 1.0, s[54:55]
	v_cndmask_b32_e64 v28, 0, 1.0, vcc
	v_cmp_lt_i32_e32 vcc, v56, v166
	v_cmp_lt_i32_e64 s[54:55], v166, v55
	v_pk_add_f32 v[28:29], v[28:29], v[42:43] neg_lo:[0,1] neg_hi:[0,1]
	v_cndmask_b32_e32 v67, 0, v30, vcc
	v_cmp_lt_i32_e32 vcc, v166, v56
	v_cndmask_b32_e64 v45, 0, v47, s[54:55]
	v_cmp_eq_u32_e64 s[54:55], v55, v166
	v_cndmask_b32_e32 v44, 0, v46, vcc
	v_cmp_lt_i32_e32 vcc, v55, v166
	v_add_u32_e32 v55, 27, v50
	v_add_u32_e32 v50, 26, v50
	v_cndmask_b32_e32 v68, 0, v31, vcc
	v_cmp_eq_u32_e32 vcc, v56, v166
	v_cndmask_b32_e64 v31, 0, 1.0, s[54:55]
	v_cmp_lt_i32_e64 s[54:55], v166, v55
	v_cndmask_b32_e64 v30, 0, 1.0, vcc
	v_cmp_lt_i32_e32 vcc, v50, v166
	v_cndmask_b32_e64 v47, 0, v49, s[54:55]
	v_cvt_pk_bf16_f32 v49, v57, v58
	v_cndmask_b32_e32 v56, 0, v32, vcc
	v_cmp_lt_i32_e32 vcc, v166, v50
	v_cmp_eq_u32_e64 s[54:55], v55, v166
	v_pk_add_f32 v[30:31], v[30:31], v[44:45] neg_lo:[0,1] neg_hi:[0,1]
	v_cndmask_b32_e32 v46, 0, v48, vcc
	v_cvt_pk_bf16_f32 v48, v51, v53
	v_cmp_lt_i32_e32 vcc, v55, v166
	v_mov_b64_e32 v[246:247], v[48:49]
	v_cvt_pk_bf16_f32 v48, v59, v60
	v_cvt_pk_bf16_f32 v49, v61, v62
	v_cndmask_b32_e32 v69, 0, v33, vcc
	v_mov_b64_e32 v[248:249], v[48:49]
	v_cvt_pk_bf16_f32 v250, v63, v64
	v_cvt_pk_bf16_f32 v251, v65, v66
	v_cvt_pk_bf16_f32 v252, v67, v68
	v_cvt_pk_bf16_f32 v253, v56, v69
	v_cvt_pk_bf16_f32 v49, v34, v35
	v_cvt_pk_bf16_f32 v4, v36, v37
	v_cvt_pk_bf16_f32 v5, v38, v39
	v_cvt_pk_bf16_f32 v34, v40, v41
	v_cvt_pk_bf16_f32 v35, v42, v43
	v_cvt_pk_bf16_f32 v48, v52, v54
	v_mov_b64_e32 v[6:7], v[34:35]
	v_cvt_pk_bf16_f32 v34, v44, v45
	v_cvt_pk_bf16_f32 v35, v46, v47
	v_mov_b64_e32 v[2:3], v[48:49]
	v_mov_b64_e32 v[8:9], v[34:35]
	v_cmp_eq_u32_e32 vcc, v50, v166
	v_cndmask_b32_e64 v33, 0, 1.0, s[54:55]
	v_cndmask_b32_e64 v32, 0, 1.0, vcc
	v_pk_add_f32 v[32:33], v[32:33], v[46:47] neg_lo:[0,1] neg_hi:[0,1]
	s_waitcnt lgkmcnt(1)
; template <int NV, bool WITHY> __device__ __forceinline__ void scan_chunk(const ScanLds& L, f32x16& st, bool hasT, int kt, int vt, int wave, int lane_, bf16* ypark = nullptr) {
;     ...
; #pragma unroll
;         for (int n = 1; n < 3; ++n) {
;             nat_store(L.BQ, Q, l31, hi); nat_store(L.BQT, QT, l31, hi); nat_store(L.BW, W, l31, hi);
;             f32x16 Qn, QTn;
; #pragma unroll
;             for (int r = 0; r < 16; ++r) { Qn[r] = 0.f; QTn[r] = 0.f; }
;             mm32<2>(W, L.BQ, 40, 0, L.BW, 40, 0, l31, hi); mm32<2>(Qn, L.BQT, 40, 0, L.BQ, 40, 0, l31, hi); mm32<2>(QTn, L.BQ, 40, 0, L.BQT, 40, 0, l31, hi); Q = Qn; QT = QTn; }
	v_mfma_f32_32x32x16_bf16 v[34:49], v[2:5], v[246:249], 0
	v_mfma_f32_32x32x16_bf16 v[50:65], v[246:249], v[2:5], 0
	s_waitcnt lgkmcnt(0)
	v_mfma_f32_32x32x16_bf16 v[34:49], v[6:9], v[250:253], v[34:49]
	v_mfma_f32_32x32x16_bf16 v[50:65], v[250:253], v[6:9], v[50:65]
	s_nop 10
	v_cvt_pk_bf16_f32 v246, v34, v35
	v_cvt_pk_bf16_f32 v247, v36, v37
	v_cvt_pk_bf16_f32 v248, v38, v39
	v_cvt_pk_bf16_f32 v249, v40, v41
	v_cvt_pk_bf16_f32 v250, v42, v43
	v_cvt_pk_bf16_f32 v251, v44, v45
	v_cvt_pk_bf16_f32 v252, v46, v47
	v_cvt_pk_bf16_f32 v253, v48, v49
	v_cvt_pk_bf16_f32 v2, v50, v51
	v_cvt_pk_bf16_f32 v3, v52, v53
	v_cvt_pk_bf16_f32 v4, v54, v55
	v_cvt_pk_bf16_f32 v5, v56, v57
	v_cvt_pk_bf16_f32 v6, v58, v59
	v_cvt_pk_bf16_f32 v7, v60, v61
	v_cvt_pk_bf16_f32 v8, v62, v63
	v_cvt_pk_bf16_f32 v9, v64, v65
	v_cvt_pk_bf16_f32 v10, v18, v19
	v_cvt_pk_bf16_f32 v11, v20, v21
	v_cvt_pk_bf16_f32 v12, v22, v23
	v_cvt_pk_bf16_f32 v13, v24, v25
	v_cvt_pk_bf16_f32 v14, v26, v27
	v_cvt_pk_bf16_f32 v15, v28, v29
	v_cvt_pk_bf16_f32 v16, v30, v31
	v_cvt_pk_bf16_f32 v17, v32, v33
	s_waitcnt lgkmcnt(1)
	v_mfma_f32_32x32x16_bf16 v[18:33], v[246:249], v[10:13], v[18:33]
	s_waitcnt lgkmcnt(2)
	v_mfma_f32_32x32x16_bf16 v[18:33], v[250:253], v[14:17], v[18:33]
	s_waitcnt lgkmcnt(1)
	v_mfma_f32_32x32x16_bf16 v[50:65], v[2:5], v[246:249], 0
	v_mfma_f32_32x32x16_bf16 v[34:49], v[246:249], v[2:5], 0
	s_waitcnt lgkmcnt(0)
	v_mfma_f32_32x32x16_bf16 v[34:49], v[250:253], v[6:9], v[34:49]
	v_mfma_f32_32x32x16_bf16 v[50:65], v[6:9], v[250:253], v[50:65]
	s_nop 10
	v_cvt_pk_bf16_f32 v2, v34, v35
	v_cvt_pk_bf16_f32 v3, v36, v37
	v_cvt_pk_bf16_f32 v4, v38, v39
	v_cvt_pk_bf16_f32 v5, v40, v41
	v_cvt_pk_bf16_f32 v6, v42, v43
	v_cvt_pk_bf16_f32 v7, v44, v45
	v_cvt_pk_bf16_f32 v34, v46, v47
	v_cvt_pk_bf16_f32 v35, v48, v49
	v_cvt_pk_bf16_f32 v50, v50, v51
	v_cvt_pk_bf16_f32 v51, v52, v53
	v_mov_b64_e32 v[8:9], v[34:35]
	v_cvt_pk_bf16_f32 v34, v18, v19
	v_cvt_pk_bf16_f32 v35, v20, v21
	v_mov_b64_e32 v[246:247], v[50:51]
	v_cvt_pk_bf16_f32 v50, v54, v55
	v_cvt_pk_bf16_f32 v51, v56, v57
	v_mov_b64_e32 v[10:11], v[34:35]
	v_cvt_pk_bf16_f32 v34, v22, v23
	v_cvt_pk_bf16_f32 v35, v24, v25
	v_mov_b64_e32 v[248:249], v[50:51]
	v_cvt_pk_bf16_f32 v50, v58, v59
	v_cvt_pk_bf16_f32 v51, v60, v61
	v_mov_b64_e32 v[12:13], v[34:35]
	v_cvt_pk_bf16_f32 v34, v26, v27
	v_cvt_pk_bf16_f32 v35, v28, v29
	v_mov_b64_e32 v[250:251], v[50:51]
	v_cvt_pk_bf16_f32 v50, v62, v63
	v_cvt_pk_bf16_f32 v51, v64, v65
	v_mov_b64_e32 v[14:15], v[34:35]
	v_cvt_pk_bf16_f32 v34, v30, v31
	v_cvt_pk_bf16_f32 v35, v32, v33
	v_mov_b64_e32 v[252:253], v[50:51]
	v_mov_b64_e32 v[16:17], v[34:35]
	s_waitcnt lgkmcnt(1)
	v_mfma_f32_32x32x16_bf16 v[18:33], v[246:249], v[10:13], v[18:33]
	s_waitcnt lgkmcnt(2)
	v_mfma_f32_32x32x16_bf16 v[18:33], v[250:253], v[14:17], v[18:33]
	s_waitcnt lgkmcnt(1)
	v_mfma_f32_32x32x16_bf16 v[50:65], v[2:5], v[246:249], 0
	v_mfma_f32_32x32x16_bf16 v[34:49], v[246:249], v[2:5], 0
	s_waitcnt lgkmcnt(0)
	v_mfma_f32_32x32x16_bf16 v[50:65], v[6:9], v[250:253], v[50:65]
	v_mfma_f32_32x32x16_bf16 v[34:49], v[250:253], v[6:9], v[34:49]

; __device__ __forceinline__ unsigned f2bf(float f) { return pk2(f, f) & 0xffffu; }
; __device__ __forceinline__ int mrow(int r, int hi) { return (r & 3) + 8 * (r >> 2) + 4 * hi; }
; template <int NV, bool WITHY> __device__ __forceinline__ void scan_chunk(const ScanLds& L, f32x16& st, bool hasT, int kt, int vt, int wave, int lane_, bf16* ypark = nullptr) {
;     ...
;     if (wave == 0) {
; #pragma unroll
;         for (int n = 3; n < 5; ++n) {
;             nat_store(L.BQ, Q, l31, hi); if (n < 4) nat_store(L.BQT, QT, l31, hi); nat_store(L.BW, W, l31, hi);
;             f32x16 Qn, QTn;
; #pragma unroll
;             for (int r = 0; r < 16; ++r) { Qn[r] = 0.f; QTn[r] = 0.f; }
;             mm32<2>(W, L.BQ, 40, 0, L.BW, 40, 0, l31, hi);
;             if (n < 4) { mm32<2>(Qn, L.BQT, 40, 0, L.BQ, 40, 0, l31, hi); mm32<2>(QTn, L.BQ, 40, 0, L.BQT, 40, 0, l31, hi); Q = Qn; QT = QTn; } }
; #pragma unroll
;         for (int r = 0; r < 16; ++r) L.TiT[mrow(r, hi) * 40 + l31] = (bf16)f2bf(W[r]);
;         __builtin_amdgcn_s_setprio(0);
.LBB0_417:
	s_nop 2
	v_cvt_pk_bf16_f32 v34, v34, v35
	v_cvt_pk_bf16_f32 v35, v36, v37
	v_cvt_pk_bf16_f32 v36, v38, v39
	v_cvt_pk_bf16_f32 v37, v40, v41
	v_mov_b64_e32 v[246:247], v[34:35]
	v_mov_b64_e32 v[248:249], v[36:37]
	v_cvt_pk_bf16_f32 v34, v42, v43
	v_cvt_pk_bf16_f32 v35, v44, v45
	v_cvt_pk_bf16_f32 v36, v46, v47
	v_cvt_pk_bf16_f32 v37, v48, v49
	v_cvt_pk_bf16_f32 v50, v50, v51
	v_cvt_pk_bf16_f32 v51, v52, v53
	v_mov_b64_e32 v[250:251], v[34:35]
	v_mov_b64_e32 v[252:253], v[36:37]
	v_cvt_pk_bf16_f32 v34, v18, v19
	v_cvt_pk_bf16_f32 v35, v20, v21
	v_mov_b64_e32 v[2:3], v[50:51]
	v_cvt_pk_bf16_f32 v50, v54, v55
	v_cvt_pk_bf16_f32 v51, v56, v57
	v_mov_b64_e32 v[10:11], v[34:35]
	v_cvt_pk_bf16_f32 v34, v22, v23
	v_cvt_pk_bf16_f32 v35, v24, v25
	v_mov_b64_e32 v[4:5], v[50:51]
	v_cvt_pk_bf16_f32 v50, v58, v59
	v_cvt_pk_bf16_f32 v51, v60, v61
	v_mov_b64_e32 v[12:13], v[34:35]
	v_cvt_pk_bf16_f32 v34, v26, v27
	v_cvt_pk_bf16_f32 v35, v28, v29
	v_mov_b64_e32 v[6:7], v[50:51]
	v_cvt_pk_bf16_f32 v50, v62, v63
	v_cvt_pk_bf16_f32 v51, v64, v65
	v_mov_b64_e32 v[14:15], v[34:35]
	v_cvt_pk_bf16_f32 v34, v30, v31
	v_cvt_pk_bf16_f32 v35, v32, v33
	v_mov_b64_e32 v[8:9], v[50:51]
	v_mov_b64_e32 v[16:17], v[34:35]
	v_add_u32_e32 v58, v172, v1
	v_add_u32_e32 v59, v171, v1
	s_waitcnt lgkmcnt(2)
	v_mfma_f32_32x32x16_bf16 v[18:33], v[2:5], v[10:13], v[18:33]
	s_waitcnt lgkmcnt(0)
	v_mfma_f32_32x32x16_bf16 v[18:33], v[6:9], v[14:17], v[18:33]
	v_add_u32_e32 v42, v173, v1
	s_waitcnt lgkmcnt(1)
	v_mfma_f32_32x32x16_bf16 v[34:49], v[246:249], v[2:5], 0
	s_waitcnt lgkmcnt(0)
	v_mfma_f32_32x32x16_bf16 v[34:49], v[250:253], v[6:9], v[34:49]
	s_nop 11
	v_cvt_pk_bf16_f32 v2, v34, v35
	v_cvt_pk_bf16_f32 v3, v36, v37
	v_cvt_pk_bf16_f32 v4, v38, v39
	v_cvt_pk_bf16_f32 v5, v40, v41
	v_cvt_pk_bf16_f32 v6, v42, v43
	v_cvt_pk_bf16_f32 v7, v44, v45
	v_cvt_pk_bf16_f32 v8, v46, v47
	v_cvt_pk_bf16_f32 v9, v48, v49
	v_cvt_pk_bf16_f32 v10, v18, v19
	v_cvt_pk_bf16_f32 v11, v20, v21
	v_cvt_pk_bf16_f32 v12, v22, v23
	v_cvt_pk_bf16_f32 v13, v24, v25
	v_cvt_pk_bf16_f32 v14, v26, v27
	v_cvt_pk_bf16_f32 v15, v28, v29
	v_cvt_pk_bf16_f32 v16, v30, v31
	v_cvt_pk_bf16_f32 v17, v32, v33
	s_waitcnt lgkmcnt(2)
	v_mfma_f32_32x32x16_bf16 v[18:33], v[2:5], v[10:13], v[18:33]
	v_lshlrev_b32_e32 v34, 1, v166
	s_waitcnt lgkmcnt(0)
	v_mfma_f32_32x32x16_bf16 v[18:33], v[6:9], v[14:17], v[18:33]
	s_nop 11
	v_cvt_pk_bf16_f32 v18, v18, s0
	s_movk_i32 s0, 0x140
	v_mul_lo_u32 v35, v168, s0
	v_add3_u32 v34, s35, v34, v35
	ds_write_b16 v34, v18
	v_cvt_pk_bf16_f32 v18, v19, s0
	ds_write_b16 v34, v18 offset:80
	v_cvt_pk_bf16_f32 v18, v20, s0
	ds_write_b16 v34, v18 offset:160
	v_cvt_pk_bf16_f32 v18, v21, s0
	ds_write_b16 v34, v18 offset:240
	v_cvt_pk_bf16_f32 v18, v22, s0
	ds_write_b16 v34, v18 offset:640
	v_cvt_pk_bf16_f32 v18, v23, s0
	ds_write_b16 v34, v18 offset:720
	v_cvt_pk_bf16_f32 v18, v24, s0
	ds_write_b16 v34, v18 offset:800
	v_cvt_pk_bf16_f32 v18, v25, s0
	ds_write_b16 v34, v18 offset:880
	v_cvt_pk_bf16_f32 v18, v26, s0
	ds_write_b16 v34, v18 offset:1280
	v_cvt_pk_bf16_f32 v18, v27, s0
	ds_write_b16 v34, v18 offset:1360
	v_cvt_pk_bf16_f32 v18, v28, s0
	ds_write_b16 v34, v18 offset:1440
	v_cvt_pk_bf16_f32 v18, v29, s0
	ds_write_b16 v34, v18 offset:1520
	v_cvt_pk_bf16_f32 v18, v30, s0
	ds_write_b16 v34, v18 offset:1920
	v_cvt_pk_bf16_f32 v18, v31, s0
	ds_write_b16 v34, v18 offset:2000
	v_cvt_pk_bf16_f32 v18, v32, s0
	ds_write_b16 v34, v18 offset:2080
	v_cvt_pk_bf16_f32 v18, v33, s0
	ds_write_b16 v34, v18 offset:2160
	s_setprio 0
	s_and_b64 vcc, exec, s[52:53]
	v_or_b32_e32 v35, s81, v166
	v_mul_u32_u24_e32 v34, 0x50, v167
	s_cbranch_vccz .LBB0_411
	s_branch .LBB0_412
